# grid barrier: non-leader workgroups poll the cross-XCD generation word directly instead of the per-XCD release word (one hop fewer per barrier)
# speedup vs baseline: 1.0239x; 1.0081x over previous
.LBB0_32:
	s_or_b64 exec, exec, s[22:23]
	v_cvt_f32_u32_e32 v5, v3
	s_waitcnt vmcnt(0)
	v_readfirstlane_b32 s2, v4
	v_sub_u32_e32 v4, 0, v3
	v_rcp_iflag_f32_e32 v5, v5
	v_add_u32_e32 v6, s2, v0
	v_mul_f32_e32 v5, 0x4f7ffffe, v5
	v_cvt_u32_f32_e32 v5, v5
	v_mul_lo_u32 v0, v4, v5
	v_mul_hi_u32 v0, v5, v0
	v_add_u32_e32 v0, v5, v0
	v_mul_hi_u32 v0, v6, v0
	v_mul_lo_u32 v4, v0, v3
	v_sub_u32_e32 v4, v6, v4
	v_add_u32_e32 v5, 1, v0
	v_cmp_ge_u32_e32 vcc, v4, v3
	s_nop 1
	v_cndmask_b32_e32 v0, v0, v5, vcc
	v_sub_u32_e32 v5, v4, v3
	v_cndmask_b32_e32 v4, v4, v5, vcc
	v_add_u32_e32 v5, 1, v0
	v_cmp_ge_u32_e32 vcc, v4, v3
	v_add_u32_e32 v4, 1, v6
	s_nop 0
	v_cndmask_b32_e32 v0, v0, v5, vcc
	v_mul_lo_u32 v5, v3, v0
	v_add_u32_e32 v3, v5, v3
	v_cmp_ne_u32_e32 vcc, v4, v3
	s_and_saveexec_b64 s[22:23], vcc
	s_xor_b64 s[22:23], exec, s[22:23]
	s_cbranch_execz .LBB0_46
	v_readlane_b32 s24, v251, 13
	v_readlane_b32 s25, v251, 14
	s_waitcnt lgkmcnt(0)
	s_nop 3
	global_load_dword v2, v1, s[24:25] sc1
	s_waitcnt vmcnt(0)
	v_cmp_eq_u32_e32 vcc, v2, v0
	s_and_saveexec_b64 s[30:31], vcc
	s_cbranch_execz .LBB0_45
	s_mov_b32 s2, 1
	s_mov_b64 s[26:27], 0
	s_branch .LBB0_36

.LBB0_771:
	s_or_b64 exec, exec, s[22:23]
	v_cvt_f32_u32_e32 v5, v3
	s_waitcnt vmcnt(0)
	v_readfirstlane_b32 s2, v4
	v_sub_u32_e32 v4, 0, v3
	v_rcp_iflag_f32_e32 v5, v5
	v_add_u32_e32 v6, s2, v0
	v_mul_f32_e32 v5, 0x4f7ffffe, v5
	v_cvt_u32_f32_e32 v5, v5
	v_mul_lo_u32 v0, v4, v5
	v_mul_hi_u32 v0, v5, v0
	v_add_u32_e32 v0, v5, v0
	v_mul_hi_u32 v0, v6, v0
	v_mul_lo_u32 v4, v0, v3
	v_sub_u32_e32 v4, v6, v4
	v_add_u32_e32 v5, 1, v0
	v_cmp_ge_u32_e32 vcc, v4, v3
	s_nop 1
	v_cndmask_b32_e32 v0, v0, v5, vcc
	v_sub_u32_e32 v5, v4, v3
	v_cndmask_b32_e32 v4, v4, v5, vcc
	v_add_u32_e32 v5, 1, v0
	v_cmp_ge_u32_e32 vcc, v4, v3
	v_add_u32_e32 v4, 1, v6
	s_nop 0
	v_cndmask_b32_e32 v0, v0, v5, vcc
	v_mul_lo_u32 v5, v3, v0
	v_add_u32_e32 v3, v5, v3
	v_cmp_ne_u32_e32 vcc, v4, v3
	s_and_saveexec_b64 s[16:17], vcc
	s_xor_b64 s[22:23], exec, s[16:17]
	s_cbranch_execz .LBB0_785
	v_readlane_b32 s16, v251, 13
	v_readlane_b32 s17, v251, 14
	s_waitcnt lgkmcnt(0)
	s_nop 3
	global_load_dword v2, v1, s[16:17] sc1
	s_waitcnt vmcnt(0)
	v_cmp_eq_u32_e32 vcc, v2, v0
	s_and_saveexec_b64 s[26:27], vcc
	s_cbranch_execz .LBB0_784
	s_mov_b32 s2, 1
	s_mov_b64 s[30:31], 0
	s_branch .LBB0_775
